# P5/P9 lean K-loops: the three/four B-fragment LDS base addresses are computed once per unit instead of every iteration (address arithmetic hoisted out of the loop)
# speedup vs baseline: 1.0039x; 1.0039x over previous
.LBB0_829:
	v_add_u32_e32 v250, 0x10000, v187
	v_add_u32_e32 v251, 0x14000, v187
	v_add_u32_e32 v252, 0x18000, v187
	v_add_u32_e32 v253, 0x1c000, v187
	s_and_b64 vcc, exec, s[4:5]
	s_cbranch_vccnz .Lq3_p5_one
	.p2align 7
.Lq3_p5_two:
	ds_read_b128 v[100:103], v250
	ds_read_b128 v[104:107], v250 offset:1024
	ds_read_b128 v[108:111], v250 offset:2048
	ds_read_b128 v[112:115], v250 offset:3072
	s_add_i32 m0, s40, 0xc000
	ds_read_b128 v[148:151], v188
	ds_read_b128 v[152:155], v188 offset:1024
	ds_read_b128 v[140:143], v188 offset:2048
	global_load_lds_dwordx4 v166, s[46:47]
	s_add_i32 m0, s40, 0xe000
	ds_read_b128 v[144:147], v188 offset:3072
	ds_read_b128 v[132:135], v188 offset:4096
	ds_read_b128 v[136:139], v188 offset:5120
	global_load_lds_dwordx4 v168, s[46:47]
	s_add_u32 s30, s46, 0xfff40080
	s_addc_u32 s31, s47, -1
	s_cmp_eq_u32 s65, 28
	s_cselect_b32 s49, s25, s31
	s_cselect_b32 s48, s24, s30
	s_cselect_b32 s31, s7, s35
	s_cselect_b32 s30, s23, s34
	s_waitcnt lgkmcnt(8)
	s_barrier
	s_waitcnt lgkmcnt(0)
	v_mfma_f32_16x16x32_bf16 v[96:99], v[100:103], v[148:151], v[96:99]
	v_mfma_f32_16x16x32_bf16 v[92:95], v[108:111], v[148:151], v[92:95]
	v_mfma_f32_16x16x32_bf16 v[88:91], v[100:103], v[140:143], v[88:91]
	v_mfma_f32_16x16x32_bf16 v[84:87], v[108:111], v[140:143], v[84:87]
	v_mfma_f32_16x16x32_bf16 v[80:83], v[100:103], v[132:135], v[80:83]
	v_mfma_f32_16x16x32_bf16 v[76:79], v[108:111], v[132:135], v[76:79]
	v_mfma_f32_16x16x32_bf16 v[96:99], v[104:107], v[152:155], v[96:99]
	v_mfma_f32_16x16x32_bf16 v[92:95], v[112:115], v[152:155], v[92:95]
	v_mfma_f32_16x16x32_bf16 v[88:91], v[104:107], v[144:147], v[88:91]
	v_mfma_f32_16x16x32_bf16 v[84:87], v[112:115], v[144:147], v[84:87]
	v_mfma_f32_16x16x32_bf16 v[80:83], v[104:107], v[136:139], v[80:83]
	v_mfma_f32_16x16x32_bf16 v[76:79], v[112:115], v[136:139], v[76:79]
	s_barrier
	s_mov_b32 m0, s41
	ds_read_b128 v[116:119], v251
	ds_read_b128 v[120:123], v251 offset:1024
	global_load_lds_dwordx4 v158, s[30:31]
	s_mov_b32 m0, s52
	ds_read_b128 v[124:127], v251 offset:2048
	ds_read_b128 v[128:131], v251 offset:3072
	global_load_lds_dwordx4 v160, s[30:31]
	s_barrier
	s_waitcnt lgkmcnt(0)
	v_mfma_f32_16x16x32_bf16 v[72:75], v[116:119], v[148:151], v[72:75]
	v_mfma_f32_16x16x32_bf16 v[68:71], v[124:127], v[148:151], v[68:71]
	v_mfma_f32_16x16x32_bf16 v[64:67], v[116:119], v[140:143], v[64:67]
	v_mfma_f32_16x16x32_bf16 v[60:63], v[124:127], v[140:143], v[60:63]
	v_mfma_f32_16x16x32_bf16 v[56:59], v[116:119], v[132:135], v[56:59]
	v_mfma_f32_16x16x32_bf16 v[52:55], v[124:127], v[132:135], v[52:55]
	v_mfma_f32_16x16x32_bf16 v[72:75], v[120:123], v[152:155], v[72:75]
	v_mfma_f32_16x16x32_bf16 v[68:71], v[128:131], v[152:155], v[68:71]
	v_mfma_f32_16x16x32_bf16 v[64:67], v[120:123], v[144:147], v[64:67]
	v_mfma_f32_16x16x32_bf16 v[60:63], v[128:131], v[144:147], v[60:63]
	v_mfma_f32_16x16x32_bf16 v[56:59], v[120:123], v[136:139], v[56:59]
	v_mfma_f32_16x16x32_bf16 v[52:55], v[128:131], v[136:139], v[52:55]
	s_barrier
	s_mov_b32 m0, s40
	ds_read_b128 v[148:151], v188 offset:16384
	ds_read_b128 v[152:155], v188 offset:17408
	ds_read_b128 v[140:143], v188 offset:18432
	global_load_lds_dwordx4 v156, s[48:49]
	s_add_i32 m0, s40, 0x2000
	ds_read_b128 v[144:147], v188 offset:19456
	ds_read_b128 v[132:135], v188 offset:20480
	ds_read_b128 v[136:139], v188 offset:21504
	global_load_lds_dwordx4 v162, s[48:49]
	s_barrier
	s_waitcnt lgkmcnt(0)
	v_mfma_f32_16x16x32_bf16 v[48:51], v[100:103], v[148:151], v[48:51]
	v_mfma_f32_16x16x32_bf16 v[44:47], v[108:111], v[148:151], v[44:47]
	v_mfma_f32_16x16x32_bf16 v[40:43], v[100:103], v[140:143], v[40:43]
	v_mfma_f32_16x16x32_bf16 v[36:39], v[108:111], v[140:143], v[36:39]
	v_mfma_f32_16x16x32_bf16 v[32:35], v[100:103], v[132:135], v[32:35]
	v_mfma_f32_16x16x32_bf16 v[28:31], v[108:111], v[132:135], v[28:31]
	v_mfma_f32_16x16x32_bf16 v[48:51], v[104:107], v[152:155], v[48:51]
	v_mfma_f32_16x16x32_bf16 v[44:47], v[112:115], v[152:155], v[44:47]
	v_mfma_f32_16x16x32_bf16 v[40:43], v[104:107], v[144:147], v[40:43]
	v_mfma_f32_16x16x32_bf16 v[36:39], v[112:115], v[144:147], v[36:39]
	v_mfma_f32_16x16x32_bf16 v[32:35], v[104:107], v[136:139], v[32:35]
	v_mfma_f32_16x16x32_bf16 v[28:31], v[112:115], v[136:139], v[28:31]
	s_barrier
	s_add_u32 s50, s30, 0x100000
	s_addc_u32 s51, s31, 0
	s_mov_b32 m0, s53
	s_nop 0
	global_load_lds_dwordx4 v158, s[50:51]
	s_mov_b32 m0, s54
	s_nop 0
	global_load_lds_dwordx4 v160, s[50:51]
	s_waitcnt vmcnt(6)
	s_barrier
	v_mfma_f32_16x16x32_bf16 v[24:27], v[116:119], v[148:151], v[24:27]
	v_mfma_f32_16x16x32_bf16 v[20:23], v[124:127], v[148:151], v[20:23]
	v_mfma_f32_16x16x32_bf16 v[16:19], v[116:119], v[140:143], v[16:19]
	v_mfma_f32_16x16x32_bf16 v[12:15], v[124:127], v[140:143], v[12:15]
	v_mfma_f32_16x16x32_bf16 v[8:11], v[116:119], v[132:135], v[8:11]
	v_mfma_f32_16x16x32_bf16 v[2:5], v[124:127], v[132:135], v[4:7]
	v_mfma_f32_16x16x32_bf16 v[24:27], v[120:123], v[152:155], v[24:27]
	v_mfma_f32_16x16x32_bf16 v[20:23], v[128:131], v[152:155], v[20:23]
	v_mfma_f32_16x16x32_bf16 v[16:19], v[120:123], v[144:147], v[16:19]
	v_mfma_f32_16x16x32_bf16 v[12:15], v[128:131], v[144:147], v[12:15]
	v_mfma_f32_16x16x32_bf16 v[8:11], v[120:123], v[136:139], v[8:11]
	v_mfma_f32_16x16x32_bf16 v[2:5], v[128:131], v[136:139], v[2:5]
	s_barrier
	ds_read_b128 v[116:119], v252
	ds_read_b128 v[120:123], v252 offset:1024
	ds_read_b128 v[124:127], v252 offset:2048
	ds_read_b128 v[128:131], v252 offset:3072
	s_add_u32 s48, s48, 0xc0000
	s_addc_u32 s49, s49, 0
	s_mov_b32 m0, s55
	ds_read_b128 v[148:151], v188 offset:32768
	ds_read_b128 v[152:155], v188 offset:33792
	ds_read_b128 v[140:143], v188 offset:34816
	global_load_lds_dwordx4 v156, s[48:49]
	s_add_i32 m0, s40, 0x6000
	ds_read_b128 v[144:147], v188 offset:35840
	ds_read_b128 v[132:135], v188 offset:36864
	ds_read_b128 v[136:139], v188 offset:37888
	global_load_lds_dwordx4 v162, s[48:49]
	s_waitcnt lgkmcnt(8)
	s_barrier
	s_waitcnt lgkmcnt(0)
	v_mfma_f32_16x16x32_bf16 v[96:99], v[116:119], v[148:151], v[96:99]
	v_mfma_f32_16x16x32_bf16 v[92:95], v[124:127], v[148:151], v[92:95]
	v_mfma_f32_16x16x32_bf16 v[88:91], v[116:119], v[140:143], v[88:91]
	v_mfma_f32_16x16x32_bf16 v[84:87], v[124:127], v[140:143], v[84:87]
	v_mfma_f32_16x16x32_bf16 v[80:83], v[116:119], v[132:135], v[80:83]
	v_mfma_f32_16x16x32_bf16 v[76:79], v[124:127], v[132:135], v[76:79]
	v_mfma_f32_16x16x32_bf16 v[96:99], v[120:123], v[152:155], v[96:99]
	v_mfma_f32_16x16x32_bf16 v[92:95], v[128:131], v[152:155], v[92:95]
	v_mfma_f32_16x16x32_bf16 v[88:91], v[120:123], v[144:147], v[88:91]
	v_mfma_f32_16x16x32_bf16 v[84:87], v[128:131], v[144:147], v[84:87]
	v_mfma_f32_16x16x32_bf16 v[80:83], v[120:123], v[136:139], v[80:83]
	v_mfma_f32_16x16x32_bf16 v[76:79], v[128:131], v[136:139], v[76:79]
	s_barrier
	s_add_u32 s50, s30, 0x80
	s_addc_u32 s51, s31, 0
	s_mov_b32 m0, s56
	ds_read_b128 v[100:103], v253
	ds_read_b128 v[104:107], v253 offset:1024
	global_load_lds_dwordx4 v158, s[50:51]
	s_mov_b32 m0, s57
	ds_read_b128 v[108:111], v253 offset:2048
	ds_read_b128 v[112:115], v253 offset:3072
	global_load_lds_dwordx4 v160, s[50:51]
	s_barrier
	s_waitcnt lgkmcnt(0)
	v_mfma_f32_16x16x32_bf16 v[72:75], v[100:103], v[148:151], v[72:75]
	v_mfma_f32_16x16x32_bf16 v[68:71], v[108:111], v[148:151], v[68:71]
	v_mfma_f32_16x16x32_bf16 v[64:67], v[100:103], v[140:143], v[64:67]
	v_mfma_f32_16x16x32_bf16 v[60:63], v[108:111], v[140:143], v[60:63]
	v_mfma_f32_16x16x32_bf16 v[56:59], v[100:103], v[132:135], v[56:59]
	v_mfma_f32_16x16x32_bf16 v[52:55], v[108:111], v[132:135], v[52:55]
	v_mfma_f32_16x16x32_bf16 v[72:75], v[104:107], v[152:155], v[72:75]
	v_mfma_f32_16x16x32_bf16 v[68:71], v[112:115], v[152:155], v[68:71]
	v_mfma_f32_16x16x32_bf16 v[64:67], v[104:107], v[144:147], v[64:67]
	v_mfma_f32_16x16x32_bf16 v[60:63], v[112:115], v[144:147], v[60:63]
	v_mfma_f32_16x16x32_bf16 v[56:59], v[104:107], v[136:139], v[56:59]
	v_mfma_f32_16x16x32_bf16 v[52:55], v[112:115], v[136:139], v[52:55]
	s_barrier
	s_add_u32 s50, s48, 0xfff40080
	s_addc_u32 s51, s49, -1
	s_mov_b32 m0, s58
	ds_read_b128 v[148:151], v188 offset:49152
	ds_read_b128 v[152:155], v188 offset:50176
	ds_read_b128 v[140:143], v188 offset:51200
	global_load_lds_dwordx4 v156, s[50:51]
	s_add_i32 m0, s40, 0xa000
	ds_read_b128 v[144:147], v188 offset:52224
	ds_read_b128 v[132:135], v188 offset:53248
	ds_read_b128 v[136:139], v188 offset:54272
	global_load_lds_dwordx4 v162, s[50:51]
	s_barrier
	s_waitcnt lgkmcnt(0)
	v_mfma_f32_16x16x32_bf16 v[48:51], v[116:119], v[148:151], v[48:51]
	v_mfma_f32_16x16x32_bf16 v[44:47], v[124:127], v[148:151], v[44:47]
	v_mfma_f32_16x16x32_bf16 v[40:43], v[116:119], v[140:143], v[40:43]
	v_mfma_f32_16x16x32_bf16 v[36:39], v[124:127], v[140:143], v[36:39]
	v_mfma_f32_16x16x32_bf16 v[32:35], v[116:119], v[132:135], v[32:35]
	v_mfma_f32_16x16x32_bf16 v[28:31], v[124:127], v[132:135], v[28:31]
	v_mfma_f32_16x16x32_bf16 v[48:51], v[120:123], v[152:155], v[48:51]
	v_mfma_f32_16x16x32_bf16 v[44:47], v[128:131], v[152:155], v[44:47]
	v_mfma_f32_16x16x32_bf16 v[40:43], v[120:123], v[144:147], v[40:43]
	v_mfma_f32_16x16x32_bf16 v[36:39], v[128:131], v[144:147], v[36:39]
	v_mfma_f32_16x16x32_bf16 v[32:35], v[120:123], v[136:139], v[32:35]
	v_mfma_f32_16x16x32_bf16 v[28:31], v[128:131], v[136:139], v[28:31]
	s_barrier
	s_add_u32 s50, s30, 0x100080
	s_addc_u32 s51, s31, 0
	s_mov_b32 m0, s59
	s_add_i32 s65, s65, 2
	global_load_lds_dwordx4 v158, s[50:51]
	s_mov_b32 m0, s60
	s_nop 0
	global_load_lds_dwordx4 v160, s[50:51]
	s_add_u32 s46, s46, 0x100
	s_addc_u32 s47, s47, 0
	s_add_u32 s34, s34, 0x100
	s_addc_u32 s35, s35, 0
	s_waitcnt vmcnt(6)
	s_barrier
	v_mfma_f32_16x16x32_bf16 v[24:27], v[100:103], v[148:151], v[24:27]
	v_mfma_f32_16x16x32_bf16 v[20:23], v[108:111], v[148:151], v[20:23]
	v_mfma_f32_16x16x32_bf16 v[16:19], v[100:103], v[140:143], v[16:19]
	v_mfma_f32_16x16x32_bf16 v[12:15], v[108:111], v[140:143], v[12:15]
	v_mfma_f32_16x16x32_bf16 v[6:9], v[100:103], v[132:135], v[8:11]
	v_mfma_f32_16x16x32_bf16 v[2:5], v[108:111], v[132:135], v[2:5]
	v_mfma_f32_16x16x32_bf16 v[24:27], v[104:107], v[152:155], v[24:27]
	v_mfma_f32_16x16x32_bf16 v[20:23], v[112:115], v[152:155], v[20:23]
	v_mfma_f32_16x16x32_bf16 v[16:19], v[104:107], v[144:147], v[16:19]
	v_mfma_f32_16x16x32_bf16 v[12:15], v[112:115], v[144:147], v[12:15]
	v_mfma_f32_16x16x32_bf16 v[8:11], v[104:107], v[136:139], v[6:9]
	v_mfma_f32_16x16x32_bf16 v[4:7], v[112:115], v[136:139], v[2:5]
	s_cmp_gt_u32 s65, 29
	s_barrier
	s_cbranch_scc0 .Lq3_p5_two
	s_branch .LBB0_845
	.p2align 7
.Lq3_p5_one:
	ds_read_b128 v[100:103], v250
	ds_read_b128 v[104:107], v250 offset:1024
	ds_read_b128 v[108:111], v250 offset:2048
	ds_read_b128 v[112:115], v250 offset:3072
	s_add_i32 m0, s40, 0xc000
	ds_read_b128 v[148:151], v188
	ds_read_b128 v[152:155], v188 offset:1024
	ds_read_b128 v[140:143], v188 offset:2048
	global_load_lds_dwordx4 v166, s[46:47]
	ds_read_b128 v[144:147], v188 offset:3072
	ds_read_b128 v[132:135], v188 offset:4096
	ds_read_b128 v[136:139], v188 offset:5120
	s_add_u32 s30, s46, 0xfff40080
	s_addc_u32 s31, s47, -1
	s_cmp_eq_u32 s65, 28
	s_cselect_b32 s49, s25, s31
	s_cselect_b32 s48, s24, s30
	s_cselect_b32 s31, s7, s35
	s_cselect_b32 s30, s23, s34
	s_waitcnt lgkmcnt(8)
	s_barrier
	s_waitcnt lgkmcnt(0)
	v_mfma_f32_16x16x32_bf16 v[96:99], v[100:103], v[148:151], v[96:99]
	v_mfma_f32_16x16x32_bf16 v[92:95], v[108:111], v[148:151], v[92:95]
	v_mfma_f32_16x16x32_bf16 v[88:91], v[100:103], v[140:143], v[88:91]
	v_mfma_f32_16x16x32_bf16 v[84:87], v[108:111], v[140:143], v[84:87]
	v_mfma_f32_16x16x32_bf16 v[80:83], v[100:103], v[132:135], v[80:83]
	v_mfma_f32_16x16x32_bf16 v[76:79], v[108:111], v[132:135], v[76:79]
	v_mfma_f32_16x16x32_bf16 v[96:99], v[104:107], v[152:155], v[96:99]
	v_mfma_f32_16x16x32_bf16 v[92:95], v[112:115], v[152:155], v[92:95]
	v_mfma_f32_16x16x32_bf16 v[88:91], v[104:107], v[144:147], v[88:91]
	v_mfma_f32_16x16x32_bf16 v[84:87], v[112:115], v[144:147], v[84:87]
	v_mfma_f32_16x16x32_bf16 v[80:83], v[104:107], v[136:139], v[80:83]
	v_mfma_f32_16x16x32_bf16 v[76:79], v[112:115], v[136:139], v[76:79]
	s_barrier
	s_mov_b32 m0, s41
	ds_read_b128 v[116:119], v251
	ds_read_b128 v[120:123], v251 offset:1024
	global_load_lds_dwordx4 v158, s[30:31]
	s_mov_b32 m0, s52
	ds_read_b128 v[124:127], v251 offset:2048
	ds_read_b128 v[128:131], v251 offset:3072
	global_load_lds_dwordx4 v160, s[30:31]
	s_barrier
	s_waitcnt lgkmcnt(0)
	v_mfma_f32_16x16x32_bf16 v[72:75], v[116:119], v[148:151], v[72:75]
	v_mfma_f32_16x16x32_bf16 v[68:71], v[124:127], v[148:151], v[68:71]
	v_mfma_f32_16x16x32_bf16 v[64:67], v[116:119], v[140:143], v[64:67]
	v_mfma_f32_16x16x32_bf16 v[60:63], v[124:127], v[140:143], v[60:63]
	v_mfma_f32_16x16x32_bf16 v[56:59], v[116:119], v[132:135], v[56:59]
	v_mfma_f32_16x16x32_bf16 v[52:55], v[124:127], v[132:135], v[52:55]
	v_mfma_f32_16x16x32_bf16 v[72:75], v[120:123], v[152:155], v[72:75]
	v_mfma_f32_16x16x32_bf16 v[68:71], v[128:131], v[152:155], v[68:71]
	v_mfma_f32_16x16x32_bf16 v[64:67], v[120:123], v[144:147], v[64:67]
	v_mfma_f32_16x16x32_bf16 v[60:63], v[128:131], v[144:147], v[60:63]
	v_mfma_f32_16x16x32_bf16 v[56:59], v[120:123], v[136:139], v[56:59]
	v_mfma_f32_16x16x32_bf16 v[52:55], v[128:131], v[136:139], v[52:55]
	s_barrier
	s_mov_b32 m0, s40
	ds_read_b128 v[148:151], v188 offset:16384
	ds_read_b128 v[152:155], v188 offset:17408
	ds_read_b128 v[140:143], v188 offset:18432
	global_load_lds_dwordx4 v156, s[48:49]
	ds_read_b128 v[144:147], v188 offset:19456
	ds_read_b128 v[132:135], v188 offset:20480
	ds_read_b128 v[136:139], v188 offset:21504
	s_barrier
	s_waitcnt lgkmcnt(0)
	v_mfma_f32_16x16x32_bf16 v[48:51], v[100:103], v[148:151], v[48:51]
	v_mfma_f32_16x16x32_bf16 v[44:47], v[108:111], v[148:151], v[44:47]
	v_mfma_f32_16x16x32_bf16 v[40:43], v[100:103], v[140:143], v[40:43]
	v_mfma_f32_16x16x32_bf16 v[36:39], v[108:111], v[140:143], v[36:39]
	v_mfma_f32_16x16x32_bf16 v[32:35], v[100:103], v[132:135], v[32:35]
	v_mfma_f32_16x16x32_bf16 v[28:31], v[108:111], v[132:135], v[28:31]
	v_mfma_f32_16x16x32_bf16 v[48:51], v[104:107], v[152:155], v[48:51]
	v_mfma_f32_16x16x32_bf16 v[44:47], v[112:115], v[152:155], v[44:47]
	v_mfma_f32_16x16x32_bf16 v[40:43], v[104:107], v[144:147], v[40:43]
	v_mfma_f32_16x16x32_bf16 v[36:39], v[112:115], v[144:147], v[36:39]
	v_mfma_f32_16x16x32_bf16 v[32:35], v[104:107], v[136:139], v[32:35]
	v_mfma_f32_16x16x32_bf16 v[28:31], v[112:115], v[136:139], v[28:31]
	s_barrier
	s_add_u32 s50, s30, 0x100000
	s_addc_u32 s51, s31, 0
	s_mov_b32 m0, s53
	s_nop 0
	global_load_lds_dwordx4 v158, s[50:51]
	s_mov_b32 m0, s54
	s_nop 0
	global_load_lds_dwordx4 v160, s[50:51]
	s_waitcnt vmcnt(5)
	s_barrier
	v_mfma_f32_16x16x32_bf16 v[24:27], v[116:119], v[148:151], v[24:27]
	v_mfma_f32_16x16x32_bf16 v[20:23], v[124:127], v[148:151], v[20:23]
	v_mfma_f32_16x16x32_bf16 v[16:19], v[116:119], v[140:143], v[16:19]
	v_mfma_f32_16x16x32_bf16 v[12:15], v[124:127], v[140:143], v[12:15]
	v_mfma_f32_16x16x32_bf16 v[8:11], v[116:119], v[132:135], v[8:11]
	v_mfma_f32_16x16x32_bf16 v[2:5], v[124:127], v[132:135], v[4:7]
	v_mfma_f32_16x16x32_bf16 v[24:27], v[120:123], v[152:155], v[24:27]
	v_mfma_f32_16x16x32_bf16 v[20:23], v[128:131], v[152:155], v[20:23]
	v_mfma_f32_16x16x32_bf16 v[16:19], v[120:123], v[144:147], v[16:19]
	v_mfma_f32_16x16x32_bf16 v[12:15], v[128:131], v[144:147], v[12:15]
	v_mfma_f32_16x16x32_bf16 v[8:11], v[120:123], v[136:139], v[8:11]
	v_mfma_f32_16x16x32_bf16 v[2:5], v[128:131], v[136:139], v[2:5]
	s_barrier
	ds_read_b128 v[116:119], v252
	ds_read_b128 v[120:123], v252 offset:1024
	ds_read_b128 v[124:127], v252 offset:2048
	ds_read_b128 v[128:131], v252 offset:3072
	s_add_u32 s48, s48, 0xc0000
	s_addc_u32 s49, s49, 0
	s_mov_b32 m0, s55
	ds_read_b128 v[148:151], v188 offset:32768
	ds_read_b128 v[152:155], v188 offset:33792
	ds_read_b128 v[140:143], v188 offset:34816
	global_load_lds_dwordx4 v156, s[48:49]
	ds_read_b128 v[144:147], v188 offset:35840
	ds_read_b128 v[132:135], v188 offset:36864
	ds_read_b128 v[136:139], v188 offset:37888
	s_waitcnt lgkmcnt(8)
	s_barrier
	s_waitcnt lgkmcnt(0)
	v_mfma_f32_16x16x32_bf16 v[96:99], v[116:119], v[148:151], v[96:99]
	v_mfma_f32_16x16x32_bf16 v[92:95], v[124:127], v[148:151], v[92:95]
	v_mfma_f32_16x16x32_bf16 v[88:91], v[116:119], v[140:143], v[88:91]
	v_mfma_f32_16x16x32_bf16 v[84:87], v[124:127], v[140:143], v[84:87]
	v_mfma_f32_16x16x32_bf16 v[80:83], v[116:119], v[132:135], v[80:83]
	v_mfma_f32_16x16x32_bf16 v[76:79], v[124:127], v[132:135], v[76:79]
	v_mfma_f32_16x16x32_bf16 v[96:99], v[120:123], v[152:155], v[96:99]
	v_mfma_f32_16x16x32_bf16 v[92:95], v[128:131], v[152:155], v[92:95]
	v_mfma_f32_16x16x32_bf16 v[88:91], v[120:123], v[144:147], v[88:91]
	v_mfma_f32_16x16x32_bf16 v[84:87], v[128:131], v[144:147], v[84:87]
	v_mfma_f32_16x16x32_bf16 v[80:83], v[120:123], v[136:139], v[80:83]
	v_mfma_f32_16x16x32_bf16 v[76:79], v[128:131], v[136:139], v[76:79]
	s_barrier
	s_add_u32 s50, s30, 0x80
	s_addc_u32 s51, s31, 0
	s_mov_b32 m0, s56
	ds_read_b128 v[100:103], v253
	ds_read_b128 v[104:107], v253 offset:1024
	global_load_lds_dwordx4 v158, s[50:51]
	s_mov_b32 m0, s57
	ds_read_b128 v[108:111], v253 offset:2048
	ds_read_b128 v[112:115], v253 offset:3072
	global_load_lds_dwordx4 v160, s[50:51]
	s_barrier
	s_waitcnt lgkmcnt(0)
	v_mfma_f32_16x16x32_bf16 v[72:75], v[100:103], v[148:151], v[72:75]
	v_mfma_f32_16x16x32_bf16 v[68:71], v[108:111], v[148:151], v[68:71]
	v_mfma_f32_16x16x32_bf16 v[64:67], v[100:103], v[140:143], v[64:67]
	v_mfma_f32_16x16x32_bf16 v[60:63], v[108:111], v[140:143], v[60:63]
	v_mfma_f32_16x16x32_bf16 v[56:59], v[100:103], v[132:135], v[56:59]
	v_mfma_f32_16x16x32_bf16 v[52:55], v[108:111], v[132:135], v[52:55]
	v_mfma_f32_16x16x32_bf16 v[72:75], v[104:107], v[152:155], v[72:75]
	v_mfma_f32_16x16x32_bf16 v[68:71], v[112:115], v[152:155], v[68:71]
	v_mfma_f32_16x16x32_bf16 v[64:67], v[104:107], v[144:147], v[64:67]
	v_mfma_f32_16x16x32_bf16 v[60:63], v[112:115], v[144:147], v[60:63]
	v_mfma_f32_16x16x32_bf16 v[56:59], v[104:107], v[136:139], v[56:59]
	v_mfma_f32_16x16x32_bf16 v[52:55], v[112:115], v[136:139], v[52:55]
	s_barrier
	s_add_u32 s50, s48, 0xfff40080
	s_addc_u32 s51, s49, -1
	s_mov_b32 m0, s58
	ds_read_b128 v[148:151], v188 offset:49152
	ds_read_b128 v[152:155], v188 offset:50176
	ds_read_b128 v[140:143], v188 offset:51200
	global_load_lds_dwordx4 v156, s[50:51]
	ds_read_b128 v[144:147], v188 offset:52224
	ds_read_b128 v[132:135], v188 offset:53248
	ds_read_b128 v[136:139], v188 offset:54272
	s_barrier
	s_waitcnt lgkmcnt(0)
	v_mfma_f32_16x16x32_bf16 v[48:51], v[116:119], v[148:151], v[48:51]
	v_mfma_f32_16x16x32_bf16 v[44:47], v[124:127], v[148:151], v[44:47]
	v_mfma_f32_16x16x32_bf16 v[40:43], v[116:119], v[140:143], v[40:43]
	v_mfma_f32_16x16x32_bf16 v[36:39], v[124:127], v[140:143], v[36:39]
	v_mfma_f32_16x16x32_bf16 v[32:35], v[116:119], v[132:135], v[32:35]
	v_mfma_f32_16x16x32_bf16 v[28:31], v[124:127], v[132:135], v[28:31]
	v_mfma_f32_16x16x32_bf16 v[48:51], v[120:123], v[152:155], v[48:51]
	v_mfma_f32_16x16x32_bf16 v[44:47], v[128:131], v[152:155], v[44:47]
	v_mfma_f32_16x16x32_bf16 v[40:43], v[120:123], v[144:147], v[40:43]
	v_mfma_f32_16x16x32_bf16 v[36:39], v[128:131], v[144:147], v[36:39]
	v_mfma_f32_16x16x32_bf16 v[32:35], v[120:123], v[136:139], v[32:35]
	v_mfma_f32_16x16x32_bf16 v[28:31], v[128:131], v[136:139], v[28:31]
	s_barrier
	s_add_u32 s50, s30, 0x100080
	s_addc_u32 s51, s31, 0
	s_mov_b32 m0, s59
	s_add_i32 s65, s65, 2
	global_load_lds_dwordx4 v158, s[50:51]
	s_mov_b32 m0, s60
	s_nop 0
	global_load_lds_dwordx4 v160, s[50:51]
	s_add_u32 s46, s46, 0x100
	s_addc_u32 s47, s47, 0
	s_add_u32 s34, s34, 0x100
	s_addc_u32 s35, s35, 0
	s_waitcnt vmcnt(5)
	s_barrier
	v_mfma_f32_16x16x32_bf16 v[24:27], v[100:103], v[148:151], v[24:27]
	v_mfma_f32_16x16x32_bf16 v[20:23], v[108:111], v[148:151], v[20:23]
	v_mfma_f32_16x16x32_bf16 v[16:19], v[100:103], v[140:143], v[16:19]
	v_mfma_f32_16x16x32_bf16 v[12:15], v[108:111], v[140:143], v[12:15]
	v_mfma_f32_16x16x32_bf16 v[6:9], v[100:103], v[132:135], v[8:11]
	v_mfma_f32_16x16x32_bf16 v[2:5], v[108:111], v[132:135], v[2:5]
	v_mfma_f32_16x16x32_bf16 v[24:27], v[104:107], v[152:155], v[24:27]
	v_mfma_f32_16x16x32_bf16 v[20:23], v[112:115], v[152:155], v[20:23]
	v_mfma_f32_16x16x32_bf16 v[16:19], v[104:107], v[144:147], v[16:19]
	v_mfma_f32_16x16x32_bf16 v[12:15], v[112:115], v[144:147], v[12:15]
	v_mfma_f32_16x16x32_bf16 v[8:11], v[104:107], v[136:139], v[6:9]
	v_mfma_f32_16x16x32_bf16 v[4:7], v[112:115], v[136:139], v[2:5]
	s_cmp_gt_u32 s65, 29
	s_barrier
	s_cbranch_scc0 .Lq3_p5_one

.LBB0_1156:
	v_add_u32_e32 v250, 0x14000, v188
	v_add_u32_e32 v251, 0x18000, v188
	v_add_u32_e32 v252, 0x1c000, v188
	s_and_b64 vcc, exec, s[2:3]
	s_cbranch_vccnz .Lq3_p9_one
	.p2align 7
.Lq3_p9_two:
	ds_read_b128 v[96:99], v189
	ds_read_b128 v[100:103], v189 offset:1024
	ds_read_b128 v[104:107], v189 offset:2048
	ds_read_b128 v[108:111], v189 offset:3072
	s_mov_b32 m0, s68
	ds_read_b128 v[144:147], v190
	ds_read_b128 v[148:151], v190 offset:1024
	ds_read_b128 v[136:139], v190 offset:2048
	global_load_lds_dwordx4 v162, s[4:5]
	s_add_i32 m0, s43, 0xe000
	ds_read_b128 v[140:143], v190 offset:3072
	ds_read_b128 v[128:131], v190 offset:4096
	ds_read_b128 v[132:135], v190 offset:5120
	global_load_lds_dwordx4 v164, s[4:5]
	s_add_u32 s4, s4, 0x100
	s_addc_u32 s5, s5, 0
	s_cmpk_eq_i32 s71, 0x54
	s_cselect_b32 s37, s25, s5
	s_cselect_b32 s36, s24, s4
	s_cselect_b32 s31, s7, s29
	s_cselect_b32 s30, s6, s28
	s_waitcnt lgkmcnt(8)
	s_barrier
	s_waitcnt lgkmcnt(0)
	v_mfma_f32_16x16x32_bf16 v[92:95], v[96:99], v[144:147], v[92:95]
	v_mfma_f32_16x16x32_bf16 v[88:91], v[104:107], v[144:147], v[88:91]
	v_mfma_f32_16x16x32_bf16 v[76:79], v[96:99], v[136:139], v[76:79]
	v_mfma_f32_16x16x32_bf16 v[72:75], v[104:107], v[136:139], v[72:75]
	v_mfma_f32_16x16x32_bf16 v[60:63], v[96:99], v[128:131], v[60:63]
	v_mfma_f32_16x16x32_bf16 v[56:59], v[104:107], v[128:131], v[56:59]
	v_mfma_f32_16x16x32_bf16 v[92:95], v[100:103], v[148:151], v[92:95]
	v_mfma_f32_16x16x32_bf16 v[88:91], v[108:111], v[148:151], v[88:91]
	v_mfma_f32_16x16x32_bf16 v[76:79], v[100:103], v[140:143], v[76:79]
	v_mfma_f32_16x16x32_bf16 v[72:75], v[108:111], v[140:143], v[72:75]
	v_mfma_f32_16x16x32_bf16 v[60:63], v[100:103], v[132:135], v[60:63]
	v_mfma_f32_16x16x32_bf16 v[56:59], v[108:111], v[132:135], v[56:59]
	s_barrier
	s_mov_b32 m0, s46
	ds_read_b128 v[112:115], v250
	ds_read_b128 v[116:119], v250 offset:1024
	global_load_lds_dwordx4 v152, s[30:31]
	s_mov_b32 m0, s47
	ds_read_b128 v[120:123], v250 offset:2048
	ds_read_b128 v[124:127], v250 offset:3072
	global_load_lds_dwordx4 v154, s[30:31]
	s_barrier
	s_waitcnt lgkmcnt(0)
	v_mfma_f32_16x16x32_bf16 v[84:87], v[112:115], v[144:147], v[84:87]
	v_mfma_f32_16x16x32_bf16 v[80:83], v[120:123], v[144:147], v[80:83]
	v_mfma_f32_16x16x32_bf16 v[68:71], v[112:115], v[136:139], v[68:71]
	v_mfma_f32_16x16x32_bf16 v[64:67], v[120:123], v[136:139], v[64:67]
	v_mfma_f32_16x16x32_bf16 v[52:55], v[112:115], v[128:131], v[52:55]
	v_mfma_f32_16x16x32_bf16 v[48:51], v[120:123], v[128:131], v[48:51]
	v_mfma_f32_16x16x32_bf16 v[84:87], v[116:119], v[148:151], v[84:87]
	v_mfma_f32_16x16x32_bf16 v[80:83], v[124:127], v[148:151], v[80:83]
	v_mfma_f32_16x16x32_bf16 v[68:71], v[116:119], v[140:143], v[68:71]
	v_mfma_f32_16x16x32_bf16 v[64:67], v[124:127], v[140:143], v[64:67]
	v_mfma_f32_16x16x32_bf16 v[52:55], v[116:119], v[132:135], v[52:55]
	v_mfma_f32_16x16x32_bf16 v[48:51], v[124:127], v[132:135], v[48:51]
	s_barrier
	s_mov_b32 m0, s43
	ds_read_b128 v[144:147], v190 offset:16384
	ds_read_b128 v[148:151], v190 offset:17408
	ds_read_b128 v[136:139], v190 offset:18432
	global_load_lds_dwordx4 v152, s[36:37]
	s_add_i32 m0, s43, 0x2000
	ds_read_b128 v[140:143], v190 offset:19456
	ds_read_b128 v[128:131], v190 offset:20480
	ds_read_b128 v[132:135], v190 offset:21504
	global_load_lds_dwordx4 v154, s[36:37]
	s_barrier
	s_waitcnt lgkmcnt(0)
	v_mfma_f32_16x16x32_bf16 v[44:47], v[96:99], v[144:147], v[44:47]
	v_mfma_f32_16x16x32_bf16 v[40:43], v[104:107], v[144:147], v[40:43]
	v_mfma_f32_16x16x32_bf16 v[28:31], v[96:99], v[136:139], v[28:31]
	v_mfma_f32_16x16x32_bf16 v[24:27], v[104:107], v[136:139], v[24:27]
	v_mfma_f32_16x16x32_bf16 v[12:15], v[96:99], v[128:131], v[12:15]
	v_mfma_f32_16x16x32_bf16 v[8:11], v[104:107], v[128:131], v[8:11]
	v_mfma_f32_16x16x32_bf16 v[44:47], v[100:103], v[148:151], v[44:47]
	v_mfma_f32_16x16x32_bf16 v[40:43], v[108:111], v[148:151], v[40:43]
	v_mfma_f32_16x16x32_bf16 v[28:31], v[100:103], v[140:143], v[28:31]
	v_mfma_f32_16x16x32_bf16 v[24:27], v[108:111], v[140:143], v[24:27]
	v_mfma_f32_16x16x32_bf16 v[12:15], v[100:103], v[132:135], v[12:15]
	v_mfma_f32_16x16x32_bf16 v[8:11], v[108:111], v[132:135], v[8:11]
	s_barrier
	s_add_u32 s34, s30, 0x160000
	s_addc_u32 s35, s31, 0
	s_mov_b32 m0, s48
	s_nop 0
	global_load_lds_dwordx4 v152, s[34:35]
	s_mov_b32 m0, s49
	s_nop 0
	global_load_lds_dwordx4 v154, s[34:35]
	s_waitcnt vmcnt(6)
	s_barrier
	v_mfma_f32_16x16x32_bf16 v[36:39], v[112:115], v[144:147], v[36:39]
	v_mfma_f32_16x16x32_bf16 v[32:35], v[120:123], v[144:147], v[32:35]
	v_mfma_f32_16x16x32_bf16 v[20:23], v[112:115], v[136:139], v[20:23]
	v_mfma_f32_16x16x32_bf16 v[16:19], v[120:123], v[136:139], v[16:19]
	v_mfma_f32_16x16x32_bf16 v[4:7], v[112:115], v[128:131], v[4:7]
	v_mfma_f32_16x16x32_bf16 v[0:3], v[120:123], v[128:131], v[0:3]
	v_mfma_f32_16x16x32_bf16 v[36:39], v[116:119], v[148:151], v[36:39]
	v_mfma_f32_16x16x32_bf16 v[32:35], v[124:127], v[148:151], v[32:35]
	v_mfma_f32_16x16x32_bf16 v[20:23], v[116:119], v[140:143], v[20:23]
	v_mfma_f32_16x16x32_bf16 v[16:19], v[124:127], v[140:143], v[16:19]
	v_mfma_f32_16x16x32_bf16 v[4:7], v[116:119], v[132:135], v[4:7]
	v_mfma_f32_16x16x32_bf16 v[0:3], v[124:127], v[132:135], v[0:3]
	s_barrier
	ds_read_b128 v[112:115], v251
	ds_read_b128 v[116:119], v251 offset:1024
	ds_read_b128 v[120:123], v251 offset:2048
	ds_read_b128 v[124:127], v251 offset:3072
	s_add_u32 s36, s36, 0x108000
	s_addc_u32 s37, s37, 0
	s_mov_b32 m0, s50
	ds_read_b128 v[144:147], v190 offset:32768
	ds_read_b128 v[148:151], v190 offset:33792
	ds_read_b128 v[136:139], v190 offset:34816
	global_load_lds_dwordx4 v152, s[36:37]
	s_add_i32 m0, s43, 0x6000
	ds_read_b128 v[140:143], v190 offset:35840
	ds_read_b128 v[128:131], v190 offset:36864
	ds_read_b128 v[132:135], v190 offset:37888
	global_load_lds_dwordx4 v154, s[36:37]
	s_waitcnt lgkmcnt(8)
	s_barrier
	s_waitcnt lgkmcnt(0)
	v_mfma_f32_16x16x32_bf16 v[92:95], v[112:115], v[144:147], v[92:95]
	v_mfma_f32_16x16x32_bf16 v[88:91], v[120:123], v[144:147], v[88:91]
	v_mfma_f32_16x16x32_bf16 v[76:79], v[112:115], v[136:139], v[76:79]
	v_mfma_f32_16x16x32_bf16 v[72:75], v[120:123], v[136:139], v[72:75]
	v_mfma_f32_16x16x32_bf16 v[60:63], v[112:115], v[128:131], v[60:63]
	v_mfma_f32_16x16x32_bf16 v[56:59], v[120:123], v[128:131], v[56:59]
	v_mfma_f32_16x16x32_bf16 v[92:95], v[116:119], v[148:151], v[92:95]
	v_mfma_f32_16x16x32_bf16 v[88:91], v[124:127], v[148:151], v[88:91]
	v_mfma_f32_16x16x32_bf16 v[76:79], v[116:119], v[140:143], v[76:79]
	v_mfma_f32_16x16x32_bf16 v[72:75], v[124:127], v[140:143], v[72:75]
	v_mfma_f32_16x16x32_bf16 v[60:63], v[116:119], v[132:135], v[60:63]
	v_mfma_f32_16x16x32_bf16 v[56:59], v[124:127], v[132:135], v[56:59]
	s_barrier
	s_add_u32 s34, s30, 0x80
	s_addc_u32 s35, s31, 0
	s_mov_b32 m0, s51
	ds_read_b128 v[96:99], v252
	ds_read_b128 v[100:103], v252 offset:1024
	global_load_lds_dwordx4 v152, s[34:35]
	s_mov_b32 m0, s52
	ds_read_b128 v[104:107], v252 offset:2048
	ds_read_b128 v[108:111], v252 offset:3072
	global_load_lds_dwordx4 v154, s[34:35]
	s_barrier
	s_waitcnt lgkmcnt(0)
	v_mfma_f32_16x16x32_bf16 v[84:87], v[96:99], v[144:147], v[84:87]
	v_mfma_f32_16x16x32_bf16 v[80:83], v[104:107], v[144:147], v[80:83]
	v_mfma_f32_16x16x32_bf16 v[68:71], v[96:99], v[136:139], v[68:71]
	v_mfma_f32_16x16x32_bf16 v[64:67], v[104:107], v[136:139], v[64:67]
	v_mfma_f32_16x16x32_bf16 v[52:55], v[96:99], v[128:131], v[52:55]
	v_mfma_f32_16x16x32_bf16 v[48:51], v[104:107], v[128:131], v[48:51]
	v_mfma_f32_16x16x32_bf16 v[84:87], v[100:103], v[148:151], v[84:87]
	v_mfma_f32_16x16x32_bf16 v[80:83], v[108:111], v[148:151], v[80:83]
	v_mfma_f32_16x16x32_bf16 v[68:71], v[100:103], v[140:143], v[68:71]
	v_mfma_f32_16x16x32_bf16 v[64:67], v[108:111], v[140:143], v[64:67]
	v_mfma_f32_16x16x32_bf16 v[52:55], v[100:103], v[132:135], v[52:55]
	v_mfma_f32_16x16x32_bf16 v[48:51], v[108:111], v[132:135], v[48:51]
	s_barrier
	s_add_u32 s34, s36, 0xffef8080
	s_addc_u32 s35, s37, -1
	s_mov_b32 m0, s53
	ds_read_b128 v[144:147], v190 offset:49152
	ds_read_b128 v[148:151], v190 offset:50176
	ds_read_b128 v[136:139], v190 offset:51200
	global_load_lds_dwordx4 v152, s[34:35]
	s_add_i32 m0, s43, 0xa000
	ds_read_b128 v[140:143], v190 offset:52224
	ds_read_b128 v[128:131], v190 offset:53248
	ds_read_b128 v[132:135], v190 offset:54272
	global_load_lds_dwordx4 v154, s[34:35]
	s_barrier
	s_waitcnt lgkmcnt(0)
	v_mfma_f32_16x16x32_bf16 v[44:47], v[112:115], v[144:147], v[44:47]
	v_mfma_f32_16x16x32_bf16 v[40:43], v[120:123], v[144:147], v[40:43]
	v_mfma_f32_16x16x32_bf16 v[28:31], v[112:115], v[136:139], v[28:31]
	v_mfma_f32_16x16x32_bf16 v[24:27], v[120:123], v[136:139], v[24:27]
	v_mfma_f32_16x16x32_bf16 v[12:15], v[112:115], v[128:131], v[12:15]
	v_mfma_f32_16x16x32_bf16 v[8:11], v[120:123], v[128:131], v[8:11]
	v_mfma_f32_16x16x32_bf16 v[44:47], v[116:119], v[148:151], v[44:47]
	v_mfma_f32_16x16x32_bf16 v[40:43], v[124:127], v[148:151], v[40:43]
	v_mfma_f32_16x16x32_bf16 v[28:31], v[116:119], v[140:143], v[28:31]
	v_mfma_f32_16x16x32_bf16 v[24:27], v[124:127], v[140:143], v[24:27]
	v_mfma_f32_16x16x32_bf16 v[12:15], v[116:119], v[132:135], v[12:15]
	v_mfma_f32_16x16x32_bf16 v[8:11], v[124:127], v[132:135], v[8:11]
	s_barrier
	s_add_u32 s34, s30, 0x160080
	s_addc_u32 s35, s31, 0
	s_mov_b32 m0, s54
	s_add_i32 s71, s71, 2
	global_load_lds_dwordx4 v152, s[34:35]
	s_mov_b32 m0, s55
	s_nop 0
	global_load_lds_dwordx4 v154, s[34:35]
	s_add_u32 s28, s28, 0x100
	s_addc_u32 s29, s29, 0
	s_waitcnt vmcnt(6)
	s_barrier
	v_mfma_f32_16x16x32_bf16 v[36:39], v[96:99], v[144:147], v[36:39]
	v_mfma_f32_16x16x32_bf16 v[32:35], v[104:107], v[144:147], v[32:35]
	v_mfma_f32_16x16x32_bf16 v[20:23], v[96:99], v[136:139], v[20:23]
	v_mfma_f32_16x16x32_bf16 v[16:19], v[104:107], v[136:139], v[16:19]
	v_mfma_f32_16x16x32_bf16 v[4:7], v[96:99], v[128:131], v[4:7]
	v_mfma_f32_16x16x32_bf16 v[0:3], v[104:107], v[128:131], v[0:3]
	v_mfma_f32_16x16x32_bf16 v[36:39], v[100:103], v[148:151], v[36:39]
	v_mfma_f32_16x16x32_bf16 v[32:35], v[108:111], v[148:151], v[32:35]
	v_mfma_f32_16x16x32_bf16 v[20:23], v[100:103], v[140:143], v[20:23]
	v_mfma_f32_16x16x32_bf16 v[16:19], v[108:111], v[140:143], v[16:19]
	v_mfma_f32_16x16x32_bf16 v[4:7], v[100:103], v[132:135], v[4:7]
	v_mfma_f32_16x16x32_bf16 v[0:3], v[108:111], v[132:135], v[0:3]
	s_cmpk_gt_u32 s71, 0x55
	s_barrier
	s_cbranch_scc0 .Lq3_p9_two
	s_branch .LBB0_1172
	.p2align 7
.Lq3_p9_one:
	ds_read_b128 v[96:99], v189
	ds_read_b128 v[100:103], v189 offset:1024
	ds_read_b128 v[104:107], v189 offset:2048
	ds_read_b128 v[108:111], v189 offset:3072
	s_mov_b32 m0, s68
	ds_read_b128 v[144:147], v190
	ds_read_b128 v[148:151], v190 offset:1024
	ds_read_b128 v[136:139], v190 offset:2048
	global_load_lds_dwordx4 v162, s[4:5]
	ds_read_b128 v[140:143], v190 offset:3072
	ds_read_b128 v[128:131], v190 offset:4096
	ds_read_b128 v[132:135], v190 offset:5120
	s_add_u32 s4, s4, 0x100
	s_addc_u32 s5, s5, 0
	s_cmpk_eq_i32 s71, 0x54
	s_cselect_b32 s37, s25, s5
	s_cselect_b32 s36, s24, s4
	s_cselect_b32 s31, s7, s29
	s_cselect_b32 s30, s6, s28
	s_waitcnt lgkmcnt(8)
	s_barrier
	s_waitcnt lgkmcnt(0)
	v_mfma_f32_16x16x32_bf16 v[92:95], v[96:99], v[144:147], v[92:95]
	v_mfma_f32_16x16x32_bf16 v[88:91], v[104:107], v[144:147], v[88:91]
	v_mfma_f32_16x16x32_bf16 v[76:79], v[96:99], v[136:139], v[76:79]
	v_mfma_f32_16x16x32_bf16 v[72:75], v[104:107], v[136:139], v[72:75]
	v_mfma_f32_16x16x32_bf16 v[60:63], v[96:99], v[128:131], v[60:63]
	v_mfma_f32_16x16x32_bf16 v[56:59], v[104:107], v[128:131], v[56:59]
	v_mfma_f32_16x16x32_bf16 v[92:95], v[100:103], v[148:151], v[92:95]
	v_mfma_f32_16x16x32_bf16 v[88:91], v[108:111], v[148:151], v[88:91]
	v_mfma_f32_16x16x32_bf16 v[76:79], v[100:103], v[140:143], v[76:79]
	v_mfma_f32_16x16x32_bf16 v[72:75], v[108:111], v[140:143], v[72:75]
	v_mfma_f32_16x16x32_bf16 v[60:63], v[100:103], v[132:135], v[60:63]
	v_mfma_f32_16x16x32_bf16 v[56:59], v[108:111], v[132:135], v[56:59]
	s_barrier
	s_mov_b32 m0, s46
	ds_read_b128 v[112:115], v250
	ds_read_b128 v[116:119], v250 offset:1024
	global_load_lds_dwordx4 v152, s[30:31]
	s_mov_b32 m0, s47
	ds_read_b128 v[120:123], v250 offset:2048
	ds_read_b128 v[124:127], v250 offset:3072
	global_load_lds_dwordx4 v154, s[30:31]
	s_barrier
	s_waitcnt lgkmcnt(0)
	v_mfma_f32_16x16x32_bf16 v[84:87], v[112:115], v[144:147], v[84:87]
	v_mfma_f32_16x16x32_bf16 v[80:83], v[120:123], v[144:147], v[80:83]
	v_mfma_f32_16x16x32_bf16 v[68:71], v[112:115], v[136:139], v[68:71]
	v_mfma_f32_16x16x32_bf16 v[64:67], v[120:123], v[136:139], v[64:67]
	v_mfma_f32_16x16x32_bf16 v[52:55], v[112:115], v[128:131], v[52:55]
	v_mfma_f32_16x16x32_bf16 v[48:51], v[120:123], v[128:131], v[48:51]
	v_mfma_f32_16x16x32_bf16 v[84:87], v[116:119], v[148:151], v[84:87]
	v_mfma_f32_16x16x32_bf16 v[80:83], v[124:127], v[148:151], v[80:83]
	v_mfma_f32_16x16x32_bf16 v[68:71], v[116:119], v[140:143], v[68:71]
	v_mfma_f32_16x16x32_bf16 v[64:67], v[124:127], v[140:143], v[64:67]
	v_mfma_f32_16x16x32_bf16 v[52:55], v[116:119], v[132:135], v[52:55]
	v_mfma_f32_16x16x32_bf16 v[48:51], v[124:127], v[132:135], v[48:51]
	s_barrier
	s_mov_b32 m0, s43
	ds_read_b128 v[144:147], v190 offset:16384
	ds_read_b128 v[148:151], v190 offset:17408
	ds_read_b128 v[136:139], v190 offset:18432
	global_load_lds_dwordx4 v152, s[36:37]
	ds_read_b128 v[140:143], v190 offset:19456
	ds_read_b128 v[128:131], v190 offset:20480
	ds_read_b128 v[132:135], v190 offset:21504
	s_barrier
	s_waitcnt lgkmcnt(0)
	v_mfma_f32_16x16x32_bf16 v[44:47], v[96:99], v[144:147], v[44:47]
	v_mfma_f32_16x16x32_bf16 v[40:43], v[104:107], v[144:147], v[40:43]
	v_mfma_f32_16x16x32_bf16 v[28:31], v[96:99], v[136:139], v[28:31]
	v_mfma_f32_16x16x32_bf16 v[24:27], v[104:107], v[136:139], v[24:27]
	v_mfma_f32_16x16x32_bf16 v[12:15], v[96:99], v[128:131], v[12:15]
	v_mfma_f32_16x16x32_bf16 v[8:11], v[104:107], v[128:131], v[8:11]
	v_mfma_f32_16x16x32_bf16 v[44:47], v[100:103], v[148:151], v[44:47]
	v_mfma_f32_16x16x32_bf16 v[40:43], v[108:111], v[148:151], v[40:43]
	v_mfma_f32_16x16x32_bf16 v[28:31], v[100:103], v[140:143], v[28:31]
	v_mfma_f32_16x16x32_bf16 v[24:27], v[108:111], v[140:143], v[24:27]
	v_mfma_f32_16x16x32_bf16 v[12:15], v[100:103], v[132:135], v[12:15]
	v_mfma_f32_16x16x32_bf16 v[8:11], v[108:111], v[132:135], v[8:11]
	s_barrier
	s_add_u32 s34, s30, 0x160000
	s_addc_u32 s35, s31, 0
	s_mov_b32 m0, s48
	s_nop 0
	global_load_lds_dwordx4 v152, s[34:35]
	s_mov_b32 m0, s49
	s_nop 0
	global_load_lds_dwordx4 v154, s[34:35]
	s_waitcnt vmcnt(5)
	s_barrier
	v_mfma_f32_16x16x32_bf16 v[36:39], v[112:115], v[144:147], v[36:39]
	v_mfma_f32_16x16x32_bf16 v[32:35], v[120:123], v[144:147], v[32:35]
	v_mfma_f32_16x16x32_bf16 v[20:23], v[112:115], v[136:139], v[20:23]
	v_mfma_f32_16x16x32_bf16 v[16:19], v[120:123], v[136:139], v[16:19]
	v_mfma_f32_16x16x32_bf16 v[4:7], v[112:115], v[128:131], v[4:7]
	v_mfma_f32_16x16x32_bf16 v[0:3], v[120:123], v[128:131], v[0:3]
	v_mfma_f32_16x16x32_bf16 v[36:39], v[116:119], v[148:151], v[36:39]
	v_mfma_f32_16x16x32_bf16 v[32:35], v[124:127], v[148:151], v[32:35]
	v_mfma_f32_16x16x32_bf16 v[20:23], v[116:119], v[140:143], v[20:23]
	v_mfma_f32_16x16x32_bf16 v[16:19], v[124:127], v[140:143], v[16:19]
	v_mfma_f32_16x16x32_bf16 v[4:7], v[116:119], v[132:135], v[4:7]
	v_mfma_f32_16x16x32_bf16 v[0:3], v[124:127], v[132:135], v[0:3]
	s_barrier
	ds_read_b128 v[112:115], v251
	ds_read_b128 v[116:119], v251 offset:1024
	ds_read_b128 v[120:123], v251 offset:2048
	ds_read_b128 v[124:127], v251 offset:3072
	s_add_u32 s36, s36, 0x108000
	s_addc_u32 s37, s37, 0
	s_mov_b32 m0, s50
	ds_read_b128 v[144:147], v190 offset:32768
	ds_read_b128 v[148:151], v190 offset:33792
	ds_read_b128 v[136:139], v190 offset:34816
	global_load_lds_dwordx4 v152, s[36:37]
	ds_read_b128 v[140:143], v190 offset:35840
	ds_read_b128 v[128:131], v190 offset:36864
	ds_read_b128 v[132:135], v190 offset:37888
	s_waitcnt lgkmcnt(8)
	s_barrier
	s_waitcnt lgkmcnt(0)
	v_mfma_f32_16x16x32_bf16 v[92:95], v[112:115], v[144:147], v[92:95]
	v_mfma_f32_16x16x32_bf16 v[88:91], v[120:123], v[144:147], v[88:91]
	v_mfma_f32_16x16x32_bf16 v[76:79], v[112:115], v[136:139], v[76:79]
	v_mfma_f32_16x16x32_bf16 v[72:75], v[120:123], v[136:139], v[72:75]
	v_mfma_f32_16x16x32_bf16 v[60:63], v[112:115], v[128:131], v[60:63]
	v_mfma_f32_16x16x32_bf16 v[56:59], v[120:123], v[128:131], v[56:59]
	v_mfma_f32_16x16x32_bf16 v[92:95], v[116:119], v[148:151], v[92:95]
	v_mfma_f32_16x16x32_bf16 v[88:91], v[124:127], v[148:151], v[88:91]
	v_mfma_f32_16x16x32_bf16 v[76:79], v[116:119], v[140:143], v[76:79]
	v_mfma_f32_16x16x32_bf16 v[72:75], v[124:127], v[140:143], v[72:75]
	v_mfma_f32_16x16x32_bf16 v[60:63], v[116:119], v[132:135], v[60:63]
	v_mfma_f32_16x16x32_bf16 v[56:59], v[124:127], v[132:135], v[56:59]
	s_barrier
	s_add_u32 s34, s30, 0x80
	s_addc_u32 s35, s31, 0
	s_mov_b32 m0, s51
	ds_read_b128 v[96:99], v252
	ds_read_b128 v[100:103], v252 offset:1024
	global_load_lds_dwordx4 v152, s[34:35]
	s_mov_b32 m0, s52
	ds_read_b128 v[104:107], v252 offset:2048
	ds_read_b128 v[108:111], v252 offset:3072
	global_load_lds_dwordx4 v154, s[34:35]
	s_barrier
	s_waitcnt lgkmcnt(0)
	v_mfma_f32_16x16x32_bf16 v[84:87], v[96:99], v[144:147], v[84:87]
	v_mfma_f32_16x16x32_bf16 v[80:83], v[104:107], v[144:147], v[80:83]
	v_mfma_f32_16x16x32_bf16 v[68:71], v[96:99], v[136:139], v[68:71]
	v_mfma_f32_16x16x32_bf16 v[64:67], v[104:107], v[136:139], v[64:67]
	v_mfma_f32_16x16x32_bf16 v[52:55], v[96:99], v[128:131], v[52:55]
	v_mfma_f32_16x16x32_bf16 v[48:51], v[104:107], v[128:131], v[48:51]
	v_mfma_f32_16x16x32_bf16 v[84:87], v[100:103], v[148:151], v[84:87]
	v_mfma_f32_16x16x32_bf16 v[80:83], v[108:111], v[148:151], v[80:83]
	v_mfma_f32_16x16x32_bf16 v[68:71], v[100:103], v[140:143], v[68:71]
	v_mfma_f32_16x16x32_bf16 v[64:67], v[108:111], v[140:143], v[64:67]
	v_mfma_f32_16x16x32_bf16 v[52:55], v[100:103], v[132:135], v[52:55]
	v_mfma_f32_16x16x32_bf16 v[48:51], v[108:111], v[132:135], v[48:51]
	s_barrier
	s_add_u32 s34, s36, 0xffef8080
	s_addc_u32 s35, s37, -1
	s_mov_b32 m0, s53
	ds_read_b128 v[144:147], v190 offset:49152
	ds_read_b128 v[148:151], v190 offset:50176
	ds_read_b128 v[136:139], v190 offset:51200
	global_load_lds_dwordx4 v152, s[34:35]
	ds_read_b128 v[140:143], v190 offset:52224
	ds_read_b128 v[128:131], v190 offset:53248
	ds_read_b128 v[132:135], v190 offset:54272
	s_barrier
	s_waitcnt lgkmcnt(0)
	v_mfma_f32_16x16x32_bf16 v[44:47], v[112:115], v[144:147], v[44:47]
	v_mfma_f32_16x16x32_bf16 v[40:43], v[120:123], v[144:147], v[40:43]
	v_mfma_f32_16x16x32_bf16 v[28:31], v[112:115], v[136:139], v[28:31]
	v_mfma_f32_16x16x32_bf16 v[24:27], v[120:123], v[136:139], v[24:27]
	v_mfma_f32_16x16x32_bf16 v[12:15], v[112:115], v[128:131], v[12:15]
	v_mfma_f32_16x16x32_bf16 v[8:11], v[120:123], v[128:131], v[8:11]
	v_mfma_f32_16x16x32_bf16 v[44:47], v[116:119], v[148:151], v[44:47]
	v_mfma_f32_16x16x32_bf16 v[40:43], v[124:127], v[148:151], v[40:43]
	v_mfma_f32_16x16x32_bf16 v[28:31], v[116:119], v[140:143], v[28:31]
	v_mfma_f32_16x16x32_bf16 v[24:27], v[124:127], v[140:143], v[24:27]
	v_mfma_f32_16x16x32_bf16 v[12:15], v[116:119], v[132:135], v[12:15]
	v_mfma_f32_16x16x32_bf16 v[8:11], v[124:127], v[132:135], v[8:11]
	s_barrier
	s_add_u32 s34, s30, 0x160080
	s_addc_u32 s35, s31, 0
	s_mov_b32 m0, s54
	s_add_i32 s71, s71, 2
	global_load_lds_dwordx4 v152, s[34:35]
	s_mov_b32 m0, s55
	s_nop 0
	global_load_lds_dwordx4 v154, s[34:35]
	s_add_u32 s28, s28, 0x100
	s_addc_u32 s29, s29, 0
	s_waitcnt vmcnt(5)
	s_barrier
	v_mfma_f32_16x16x32_bf16 v[36:39], v[96:99], v[144:147], v[36:39]
	v_mfma_f32_16x16x32_bf16 v[32:35], v[104:107], v[144:147], v[32:35]
	v_mfma_f32_16x16x32_bf16 v[20:23], v[96:99], v[136:139], v[20:23]
	v_mfma_f32_16x16x32_bf16 v[16:19], v[104:107], v[136:139], v[16:19]
	v_mfma_f32_16x16x32_bf16 v[4:7], v[96:99], v[128:131], v[4:7]
	v_mfma_f32_16x16x32_bf16 v[0:3], v[104:107], v[128:131], v[0:3]
	v_mfma_f32_16x16x32_bf16 v[36:39], v[100:103], v[148:151], v[36:39]
	v_mfma_f32_16x16x32_bf16 v[32:35], v[108:111], v[148:151], v[32:35]
	v_mfma_f32_16x16x32_bf16 v[20:23], v[100:103], v[140:143], v[20:23]
	v_mfma_f32_16x16x32_bf16 v[16:19], v[108:111], v[140:143], v[16:19]
	v_mfma_f32_16x16x32_bf16 v[4:7], v[100:103], v[132:135], v[4:7]
	v_mfma_f32_16x16x32_bf16 v[0:3], v[108:111], v[132:135], v[0:3]
	s_cmpk_gt_u32 s71, 0x55
	s_barrier
	s_cbranch_scc0 .Lq3_p9_one
